# attention: K and V fragment LDS reads issued up front per subtile (counted lgkmcnt) instead of read-wait-mfma chains
# speedup vs baseline: 1.0185x; 1.0108x over previous
; #define LAS __attribute__((address_space(3)))
; __device__ __forceinline__ void attn_phase(LAS unsigned char* lds, const bf16_t* qkv, bf16_t* og, float* lse, int G, int bid) {
;     ...
; #pragma unroll
;             for (int s = 0; s < 16; ++s) {
;                 sc[s] = (f32x4){0.f, 0.f, 0.f, 0.f};
;                 if (s >= wid && s <= wid + 8 && (s >= 8 || blk > 0)) {
;                     LAS unsigned char* kb = (s < 8 ? Kp : Kc) + (16 * (s & 7) + fr) * KP + 16 * fq;
; #pragma unroll
;                     for (int kk = 0; kk < 4; ++kk) {
;                         const bf16x8 kf = *(const LAS bf16x8*)(kb + 64 * kk);
;                         sc[s] = __builtin_amdgcn_mfma_f32_16x16x32_bf16(kf, Q[kk], sc[s], 0, 0, 0);
;                     }
;                 }
;             }
.LBB0_1124:
	s_and_b32 s81, s79, 1
	s_lshl_b32 s1, s81, 7
	s_add_i32 s0, s77, s78
	s_xor_b32 s82, s1, 0x80
	s_cmp_lg_u32 s0, 0
	s_cselect_b64 s[30:31], -1, 0
	s_and_b64 s[0:1], s[62:63], s[30:31]
	s_mul_i32 s80, s82, 0x110
	v_cndmask_b32_e64 v0, 0, 1, s[0:1]
	v_mov_b32_e32 v52, 0
	v_cmp_ne_u32_e64 s[38:39], 1, v0
	s_andn2_b64 vcc, exec, s[0:1]
	v_add_u32_e32 v0, s80, v154
	v_mov_b32_e32 v60, 0
	v_mov_b32_e32 v61, 0
	v_mov_b32_e32 v62, 0
	v_mov_b32_e32 v63, 0
	s_cbranch_vccnz .LBB0_1126
	ds_read_b128 v[226:229], v0
	ds_read_b128 v[230:233], v0 offset:64
	ds_read_b128 v[234:237], v0 offset:128
	ds_read_b128 v[238:241], v0 offset:192
	s_waitcnt lgkmcnt(3)
	v_mfma_f32_16x16x32_bf16 v[54:57], v[226:229], v[128:131], 0
	s_waitcnt lgkmcnt(2)
	v_mfma_f32_16x16x32_bf16 v[54:57], v[230:233], v[124:127], v[54:57]
	s_waitcnt lgkmcnt(1)
	v_mfma_f32_16x16x32_bf16 v[54:57], v[234:237], v[120:123], v[54:57]
	s_waitcnt lgkmcnt(0)
	v_mfma_f32_16x16x32_bf16 v[60:63], v[238:241], v[116:119], v[54:57]
.LBB0_1126:
	s_and_b64 s[0:1], s[4:5], s[30:31]
	v_cndmask_b32_e64 v2, 0, 1, s[0:1]
	v_cmp_ne_u32_e64 s[36:37], 1, v2
	s_andn2_b64 vcc, exec, s[0:1]
	v_mov_b32_e32 v53, 0
	v_mov_b32_e32 v54, 0
	v_mov_b32_e32 v55, 0
	s_cbranch_vccnz .LBB0_1128
	ds_read_b128 v[226:229], v0 offset:4352
	ds_read_b128 v[230:233], v0 offset:4416
	ds_read_b128 v[234:237], v0 offset:4480
	ds_read_b128 v[238:241], v0 offset:4544
	s_waitcnt lgkmcnt(3)
	v_mfma_f32_16x16x32_bf16 v[52:55], v[226:229], v[128:131], 0
	s_waitcnt lgkmcnt(2)
	v_mfma_f32_16x16x32_bf16 v[52:55], v[230:233], v[124:127], v[52:55]
	s_waitcnt lgkmcnt(1)
	v_mfma_f32_16x16x32_bf16 v[52:55], v[234:237], v[120:123], v[52:55]
	s_waitcnt lgkmcnt(0)
	v_mfma_f32_16x16x32_bf16 v[52:55], v[238:241], v[116:119], v[52:55]
.LBB0_1128:
	s_and_b64 s[0:1], s[6:7], s[30:31]
	v_cndmask_b32_e64 v2, 0, 1, s[0:1]
	v_mov_b32_e32 v56, 0
	v_cmp_ne_u32_e64 s[40:41], 1, v2
	s_andn2_b64 vcc, exec, s[0:1]
	v_mov_b32_e32 v72, 0
	v_mov_b32_e32 v73, 0
	v_mov_b32_e32 v74, 0
	v_mov_b32_e32 v75, 0
	s_cbranch_vccnz .LBB0_1130
	ds_read_b128 v[226:229], v0 offset:8704
	ds_read_b128 v[230:233], v0 offset:8768
	ds_read_b128 v[234:237], v0 offset:8832
	ds_read_b128 v[238:241], v0 offset:8896
	s_waitcnt lgkmcnt(3)
	v_mfma_f32_16x16x32_bf16 v[64:67], v[226:229], v[128:131], 0
	s_waitcnt lgkmcnt(2)
	v_mfma_f32_16x16x32_bf16 v[64:67], v[230:233], v[124:127], v[64:67]
	s_waitcnt lgkmcnt(1)
	v_mfma_f32_16x16x32_bf16 v[64:67], v[234:237], v[120:123], v[64:67]
	s_waitcnt lgkmcnt(0)
	v_mfma_f32_16x16x32_bf16 v[72:75], v[238:241], v[116:119], v[64:67]
.LBB0_1130:
	s_and_b64 s[0:1], s[8:9], s[30:31]
	v_cndmask_b32_e64 v2, 0, 1, s[0:1]
	v_cmp_ne_u32_e64 s[34:35], 1, v2
	s_andn2_b64 vcc, exec, s[0:1]
	v_mov_b32_e32 v57, 0
	v_mov_b32_e32 v58, 0
	v_mov_b32_e32 v59, 0
	s_cbranch_vccnz .LBB0_1132
	ds_read_b128 v[226:229], v0 offset:13056
	ds_read_b128 v[230:233], v0 offset:13120
	ds_read_b128 v[234:237], v0 offset:13184
	ds_read_b128 v[238:241], v0 offset:13248
	s_waitcnt lgkmcnt(3)
	v_mfma_f32_16x16x32_bf16 v[56:59], v[226:229], v[128:131], 0
	s_waitcnt lgkmcnt(2)
	v_mfma_f32_16x16x32_bf16 v[56:59], v[230:233], v[124:127], v[56:59]
	s_waitcnt lgkmcnt(1)
	v_mfma_f32_16x16x32_bf16 v[56:59], v[234:237], v[120:123], v[56:59]
	s_waitcnt lgkmcnt(0)
	v_mfma_f32_16x16x32_bf16 v[56:59], v[238:241], v[116:119], v[56:59]
.LBB0_1132:
	s_and_b64 s[0:1], s[10:11], s[30:31]
	v_cndmask_b32_e64 v2, 0, 1, s[0:1]
	v_mov_b32_e32 v64, 0
	v_cmp_ne_u32_e64 s[42:43], 1, v2
	s_andn2_b64 vcc, exec, s[0:1]
	v_mov_b32_e32 v80, 0
	v_mov_b32_e32 v81, 0
	v_mov_b32_e32 v82, 0
	v_mov_b32_e32 v83, 0
	s_cbranch_vccnz .LBB0_1134
	ds_read_b128 v[226:229], v0 offset:17408
	ds_read_b128 v[230:233], v0 offset:17472
	ds_read_b128 v[234:237], v0 offset:17536
	ds_read_b128 v[238:241], v0 offset:17600
	s_waitcnt lgkmcnt(3)
	v_mfma_f32_16x16x32_bf16 v[66:69], v[226:229], v[128:131], 0
	s_waitcnt lgkmcnt(2)
	v_mfma_f32_16x16x32_bf16 v[66:69], v[230:233], v[124:127], v[66:69]
	s_waitcnt lgkmcnt(1)
	v_mfma_f32_16x16x32_bf16 v[66:69], v[234:237], v[120:123], v[66:69]
	s_waitcnt lgkmcnt(0)
	v_mfma_f32_16x16x32_bf16 v[80:83], v[238:241], v[116:119], v[66:69]
.LBB0_1134:
	s_and_b64 s[44:45], s[12:13], s[30:31]
	v_cndmask_b32_e64 v2, 0, 1, s[44:45]
	v_cmp_ne_u32_e64 s[0:1], 1, v2
	s_andn2_b64 vcc, exec, s[44:45]
	v_mov_b32_e32 v65, 0
	v_mov_b32_e32 v66, 0
	v_mov_b32_e32 v67, 0
	s_cbranch_vccnz .LBB0_1136
	ds_read_b128 v[226:229], v0 offset:21760
	ds_read_b128 v[230:233], v0 offset:21824
	ds_read_b128 v[234:237], v0 offset:21888
	ds_read_b128 v[238:241], v0 offset:21952
	s_waitcnt lgkmcnt(3)
	v_mfma_f32_16x16x32_bf16 v[64:67], v[226:229], v[128:131], 0
	s_waitcnt lgkmcnt(2)
	v_mfma_f32_16x16x32_bf16 v[64:67], v[230:233], v[124:127], v[64:67]
	s_waitcnt lgkmcnt(1)
	v_mfma_f32_16x16x32_bf16 v[64:67], v[234:237], v[120:123], v[64:67]
	s_waitcnt lgkmcnt(0)
	v_mfma_f32_16x16x32_bf16 v[64:67], v[238:241], v[116:119], v[64:67]
.LBB0_1136:
	s_and_b64 s[46:47], s[14:15], s[30:31]
	v_cndmask_b32_e64 v2, 0, 1, s[46:47]
	v_mov_b32_e32 v68, 0
	v_cmp_ne_u32_e64 s[44:45], 1, v2
	s_andn2_b64 vcc, exec, s[46:47]
	v_mov_b32_e32 v88, 0
	v_mov_b32_e32 v89, 0
	v_mov_b32_e32 v90, 0
	v_mov_b32_e32 v91, 0
	s_cbranch_vccnz .LBB0_1138
	ds_read_b128 v[226:229], v0 offset:26112
	ds_read_b128 v[230:233], v0 offset:26176
	ds_read_b128 v[234:237], v0 offset:26240
	ds_read_b128 v[238:241], v0 offset:26304
	s_waitcnt lgkmcnt(3)
	v_mfma_f32_16x16x32_bf16 v[76:79], v[226:229], v[128:131], 0
	s_waitcnt lgkmcnt(2)
	v_mfma_f32_16x16x32_bf16 v[76:79], v[230:233], v[124:127], v[76:79]
	s_waitcnt lgkmcnt(1)
	v_mfma_f32_16x16x32_bf16 v[76:79], v[234:237], v[120:123], v[76:79]
	s_waitcnt lgkmcnt(0)
	v_mfma_f32_16x16x32_bf16 v[88:91], v[238:241], v[116:119], v[76:79]
; #define LAS __attribute__((address_space(3)))
; __device__ __forceinline__ void attn_phase(LAS unsigned char* lds, const bf16_t* qkv, bf16_t* og, float* lse, int G, int bid) {
;     ...
; #pragma unroll
;             for (int s = 0; s < 16; ++s) {
;                 sc[s] = (f32x4){0.f, 0.f, 0.f, 0.f};
;                 if (s >= wid && s <= wid + 8 && (s >= 8 || blk > 0)) {
;                     LAS unsigned char* kb = (s < 8 ? Kp : Kc) + (16 * (s & 7) + fr) * KP + 16 * fq;
; #pragma unroll
;                     for (int kk = 0; kk < 4; ++kk) {
;                         const bf16x8 kf = *(const LAS bf16x8*)(kb + 64 * kk);
;                         sc[s] = __builtin_amdgcn_mfma_f32_16x16x32_bf16(kf, Q[kk], sc[s], 0, 0, 0);
;                     }
;                 }
;             }
.LBB0_1138:
	s_and_b64 s[46:47], s[64:65], s[30:31]
	v_cndmask_b32_e64 v2, 0, 1, s[46:47]
	v_cmp_ne_u32_e64 s[30:31], 1, v2
	s_andn2_b64 vcc, exec, s[46:47]
	v_mov_b32_e32 v69, 0
	v_mov_b32_e32 v70, 0
	v_mov_b32_e32 v71, 0
	s_cbranch_vccnz .LBB0_1140
	ds_read_b128 v[226:229], v0 offset:30464
	ds_read_b128 v[230:233], v0 offset:30528
	ds_read_b128 v[234:237], v0 offset:30592
	ds_read_b128 v[238:241], v0 offset:30656
	s_waitcnt lgkmcnt(3)
	v_mfma_f32_16x16x32_bf16 v[68:71], v[226:229], v[128:131], 0
	s_waitcnt lgkmcnt(2)
	v_mfma_f32_16x16x32_bf16 v[68:71], v[230:233], v[124:127], v[68:71]
	s_waitcnt lgkmcnt(1)
	v_mfma_f32_16x16x32_bf16 v[68:71], v[234:237], v[120:123], v[68:71]
	s_waitcnt lgkmcnt(0)
	v_mfma_f32_16x16x32_bf16 v[68:71], v[238:241], v[116:119], v[68:71]
.LBB0_1140:
	s_mul_i32 s81, s81, 0x8800
	v_cndmask_b32_e64 v0, 0, 1, s[66:67]
	v_mov_b32_e32 v76, 0
	v_cmp_ne_u32_e64 s[46:47], 1, v0
	s_andn2_b64 vcc, exec, s[66:67]
	v_add_u32_e32 v0, s81, v154
	v_mov_b32_e32 v96, 0
	v_mov_b32_e32 v97, 0
	v_mov_b32_e32 v98, 0
	v_mov_b32_e32 v99, 0
	s_cbranch_vccnz .LBB0_1142
	ds_read_b128 v[226:229], v0
	ds_read_b128 v[230:233], v0 offset:64
	ds_read_b128 v[234:237], v0 offset:128
	ds_read_b128 v[238:241], v0 offset:192
	s_waitcnt lgkmcnt(3)
	v_mfma_f32_16x16x32_bf16 v[84:87], v[226:229], v[128:131], 0
	s_waitcnt lgkmcnt(2)
	v_mfma_f32_16x16x32_bf16 v[84:87], v[230:233], v[124:127], v[84:87]
	s_waitcnt lgkmcnt(1)
	v_mfma_f32_16x16x32_bf16 v[84:87], v[234:237], v[120:123], v[84:87]
	s_waitcnt lgkmcnt(0)
	v_mfma_f32_16x16x32_bf16 v[96:99], v[238:241], v[116:119], v[84:87]
.LBB0_1142:
	v_cndmask_b32_e64 v2, 0, 1, s[16:17]
	v_cmp_ne_u32_e64 s[48:49], 1, v2
	s_andn2_b64 vcc, exec, s[16:17]
	v_mov_b32_e32 v77, 0
	v_mov_b32_e32 v78, 0
	v_mov_b32_e32 v79, 0
	s_cbranch_vccnz .LBB0_1144
	ds_read_b128 v[226:229], v0 offset:4352
	ds_read_b128 v[230:233], v0 offset:4416
	ds_read_b128 v[234:237], v0 offset:4480
	ds_read_b128 v[238:241], v0 offset:4544
	s_waitcnt lgkmcnt(3)
	v_mfma_f32_16x16x32_bf16 v[76:79], v[226:229], v[128:131], 0
	s_waitcnt lgkmcnt(2)
	v_mfma_f32_16x16x32_bf16 v[76:79], v[230:233], v[124:127], v[76:79]
	s_waitcnt lgkmcnt(1)
	v_mfma_f32_16x16x32_bf16 v[76:79], v[234:237], v[120:123], v[76:79]
	s_waitcnt lgkmcnt(0)
	v_mfma_f32_16x16x32_bf16 v[76:79], v[238:241], v[116:119], v[76:79]
.LBB0_1144:
	v_cndmask_b32_e64 v2, 0, 1, s[18:19]
	v_mov_b32_e32 v84, 0
	v_cmp_ne_u32_e64 s[50:51], 1, v2
	s_andn2_b64 vcc, exec, s[18:19]
	v_mov_b32_e32 v104, 0
	v_mov_b32_e32 v105, 0
	v_mov_b32_e32 v106, 0
	v_mov_b32_e32 v107, 0
	s_cbranch_vccnz .LBB0_1146
	ds_read_b128 v[226:229], v0 offset:8704
	ds_read_b128 v[230:233], v0 offset:8768
	ds_read_b128 v[234:237], v0 offset:8832
	ds_read_b128 v[238:241], v0 offset:8896
	s_waitcnt lgkmcnt(3)
	v_mfma_f32_16x16x32_bf16 v[92:95], v[226:229], v[128:131], 0
	s_waitcnt lgkmcnt(2)
	v_mfma_f32_16x16x32_bf16 v[92:95], v[230:233], v[124:127], v[92:95]
	s_waitcnt lgkmcnt(1)
	v_mfma_f32_16x16x32_bf16 v[92:95], v[234:237], v[120:123], v[92:95]
	s_waitcnt lgkmcnt(0)
	v_mfma_f32_16x16x32_bf16 v[104:107], v[238:241], v[116:119], v[92:95]
.LBB0_1146:
	v_cndmask_b32_e64 v2, 0, 1, s[20:21]
	v_cmp_ne_u32_e64 s[52:53], 1, v2
	s_andn2_b64 vcc, exec, s[20:21]
	v_mov_b32_e32 v85, 0
	v_mov_b32_e32 v86, 0
	v_mov_b32_e32 v87, 0
	s_cbranch_vccnz .LBB0_1148
	ds_read_b128 v[226:229], v0 offset:13056
	ds_read_b128 v[230:233], v0 offset:13120
	ds_read_b128 v[234:237], v0 offset:13184
	ds_read_b128 v[238:241], v0 offset:13248
	s_waitcnt lgkmcnt(3)
	v_mfma_f32_16x16x32_bf16 v[84:87], v[226:229], v[128:131], 0
	s_waitcnt lgkmcnt(2)
	v_mfma_f32_16x16x32_bf16 v[84:87], v[230:233], v[124:127], v[84:87]
	s_waitcnt lgkmcnt(1)
	v_mfma_f32_16x16x32_bf16 v[84:87], v[234:237], v[120:123], v[84:87]
	s_waitcnt lgkmcnt(0)
	v_mfma_f32_16x16x32_bf16 v[84:87], v[238:241], v[116:119], v[84:87]
.LBB0_1148:
	v_cndmask_b32_e64 v2, 0, 1, s[22:23]
	v_mov_b32_e32 v92, 0
	v_cmp_ne_u32_e64 s[54:55], 1, v2
	s_andn2_b64 vcc, exec, s[22:23]
	v_mov_b32_e32 v108, 0
	v_mov_b32_e32 v109, 0
	v_mov_b32_e32 v110, 0
	v_mov_b32_e32 v111, 0
	s_cbranch_vccnz .LBB0_1150
	ds_read_b128 v[226:229], v0 offset:17408
	ds_read_b128 v[230:233], v0 offset:17472
	ds_read_b128 v[234:237], v0 offset:17536
	ds_read_b128 v[238:241], v0 offset:17600
	s_waitcnt lgkmcnt(3)
	v_mfma_f32_16x16x32_bf16 v[100:103], v[226:229], v[128:131], 0
	s_waitcnt lgkmcnt(2)
	v_mfma_f32_16x16x32_bf16 v[100:103], v[230:233], v[124:127], v[100:103]
	s_waitcnt lgkmcnt(1)
	v_mfma_f32_16x16x32_bf16 v[100:103], v[234:237], v[120:123], v[100:103]
	s_waitcnt lgkmcnt(0)
	v_mfma_f32_16x16x32_bf16 v[108:111], v[238:241], v[116:119], v[100:103]
.LBB0_1150:
	v_cndmask_b32_e64 v2, 0, 1, s[24:25]
	v_cmp_ne_u32_e64 s[56:57], 1, v2
	s_andn2_b64 vcc, exec, s[24:25]
	v_mov_b32_e32 v93, 0
	v_mov_b32_e32 v94, 0
	v_mov_b32_e32 v95, 0
	s_cbranch_vccnz .LBB0_1152
	ds_read_b128 v[226:229], v0 offset:21760
	ds_read_b128 v[230:233], v0 offset:21824
	ds_read_b128 v[234:237], v0 offset:21888
	ds_read_b128 v[238:241], v0 offset:21952
	s_waitcnt lgkmcnt(3)
	v_mfma_f32_16x16x32_bf16 v[92:95], v[226:229], v[128:131], 0
	s_waitcnt lgkmcnt(2)
	v_mfma_f32_16x16x32_bf16 v[92:95], v[230:233], v[124:127], v[92:95]
	s_waitcnt lgkmcnt(1)
	v_mfma_f32_16x16x32_bf16 v[92:95], v[234:237], v[120:123], v[92:95]
	s_waitcnt lgkmcnt(0)
	v_mfma_f32_16x16x32_bf16 v[92:95], v[238:241], v[116:119], v[92:95]
.LBB0_1152:
	v_cndmask_b32_e64 v2, 0, 1, s[26:27]
	v_mov_b32_e32 v100, 0
	v_cmp_ne_u32_e64 s[58:59], 1, v2
	s_andn2_b64 vcc, exec, s[26:27]
	v_mov_b32_e32 v112, 0
	v_mov_b32_e32 v113, 0
	v_mov_b32_e32 v114, 0
	v_mov_b32_e32 v115, 0
	s_cbranch_vccnz .LBB0_1154
	ds_read_b128 v[226:229], v0 offset:26112
	ds_read_b128 v[230:233], v0 offset:26176
	ds_read_b128 v[234:237], v0 offset:26240
	ds_read_b128 v[238:241], v0 offset:26304
	s_waitcnt lgkmcnt(3)
	v_mfma_f32_16x16x32_bf16 v[112:115], v[226:229], v[128:131], 0
	s_waitcnt lgkmcnt(2)
	v_mfma_f32_16x16x32_bf16 v[112:115], v[230:233], v[124:127], v[112:115]
	s_waitcnt lgkmcnt(1)
	v_mfma_f32_16x16x32_bf16 v[112:115], v[234:237], v[120:123], v[112:115]
	s_waitcnt lgkmcnt(0)
	v_mfma_f32_16x16x32_bf16 v[112:115], v[238:241], v[116:119], v[112:115]

; #define LAS __attribute__((address_space(3)))
; __device__ __forceinline__ void attn_phase(LAS unsigned char* lds, const bf16_t* qkv, bf16_t* og, float* lse, int G, int bid) {
;     ...
; #pragma unroll
;             for (int s = 0; s < 16; ++s) {
;                 sc[s] = (f32x4){0.f, 0.f, 0.f, 0.f};
;                 if (s >= wid && s <= wid + 8 && (s >= 8 || blk > 0)) {
;                     LAS unsigned char* kb = (s < 8 ? Kp : Kc) + (16 * (s & 7) + fr) * KP + 16 * fq;
; #pragma unroll
;                     for (int kk = 0; kk < 4; ++kk) {
;                         const bf16x8 kf = *(const LAS bf16x8*)(kb + 64 * kk);
;                         sc[s] = __builtin_amdgcn_mfma_f32_16x16x32_bf16(kf, Q[kk], sc[s], 0, 0, 0);
;                     }
;                 }
;             }
;             float mx = -3.0e38f;
.LBB0_1190:
	ds_read_b128 v[226:229], v0 offset:30464
	ds_read_b128 v[230:233], v0 offset:30528
	ds_read_b128 v[234:237], v0 offset:30592
	ds_read_b128 v[238:241], v0 offset:30656
	s_waitcnt lgkmcnt(3)
	v_mfma_f32_16x16x32_bf16 v[100:103], v[226:229], v[128:131], 0
	s_waitcnt lgkmcnt(2)
	v_mfma_f32_16x16x32_bf16 v[100:103], v[230:233], v[124:127], v[100:103]
	s_waitcnt lgkmcnt(1)
	v_mfma_f32_16x16x32_bf16 v[100:103], v[234:237], v[120:123], v[100:103]
	s_waitcnt lgkmcnt(0)
	v_mfma_f32_16x16x32_bf16 v[100:103], v[238:241], v[116:119], v[100:103]
	s_and_b64 vcc, exec, s[38:39]
	v_mov_b32_e32 v0, 0xff61b1e6
	s_cbranch_vccnz .LBB0_1156

; #define LAS __attribute__((address_space(3)))
; __device__ __forceinline__ unsigned cvt_pk_bf16(float lo, float hi) { unsigned r; asm volatile("v_cvt_pk_bf16_f32 %0, %1, %2" : "=v"(r) : "v"(lo), "v"(hi)); return r; }
; __device__ __forceinline__ void attn_phase(LAS unsigned char* lds, const bf16_t* qkv, bf16_t* og, float* lse, int G, int bid) {
;     ...
;             for (int ks = 0; ks < 8; ++ks) {
;                 if (2 * ks + 1 >= wid && 2 * ks <= wid + 8 && (ks >= 4 || blk > 0)) {
;                     union { u32x4 u; bf16x8 b; } P;
;                     P.u.x = cvt_pk_bf16(sc[2 * ks][0], sc[2 * ks][1]); P.u.y = cvt_pk_bf16(sc[2 * ks][2], sc[2 * ks][3]);
;                     P.u.z = cvt_pk_bf16(sc[2 * ks + 1][0], sc[2 * ks + 1][1]); P.u.w = cvt_pk_bf16(sc[2 * ks + 1][2], sc[2 * ks + 1][3]);
;                     LAS unsigned char* vb = (ks < 4 ? Vp : Vc) + (32 * (ks & 3) + 4 * fq + (fr >> 2)) * KP + 8 * (fr & 3);
; #pragma unroll
;                     for (int dt = 0; dt < 8; ++dt) {
;                         const s16x4 v0 = __builtin_amdgcn_ds_read_tr16_b64_v4i16((LAS s16x4*)(vb + 32 * dt));
;                         const s16x4 v1 = __builtin_amdgcn_ds_read_tr16_b64_v4i16((LAS s16x4*)(vb + 16 * KP + 32 * dt));
;                         const bf16x8 vf = __builtin_shufflevector(v0, v1, 0, 1, 2, 3, 4, 5, 6, 7);
;                         o[dt] = __builtin_amdgcn_mfma_f32_16x16x32_bf16(vf, P.b, o[dt], 0, 0, 0);
;                     }
;                 }
.LBB0_1224:
	v_cvt_pk_bf16_f32 v108, v180, v181
	v_cvt_pk_bf16_f32 v109, v182, v183
	v_cvt_pk_bf16_f32 v110, v179, v184
	v_cvt_pk_bf16_f32 v111, v185, v186
	ds_read_b64_tr_b16 v[192:193], v100 offset:8704
	ds_read_b64_tr_b16 v[194:195], v100 offset:13056
	ds_read_b64_tr_b16 v[196:197], v100 offset:8768
	ds_read_b64_tr_b16 v[198:199], v100 offset:13120
	ds_read_b64_tr_b16 v[200:201], v100 offset:8800
	ds_read_b64_tr_b16 v[202:203], v100 offset:13152
	ds_read_b64_tr_b16 v[204:205], v100 offset:8832
	ds_read_b64_tr_b16 v[206:207], v100 offset:13184
	ds_read_b64_tr_b16 v[208:209], v100 offset:8864
	ds_read_b64_tr_b16 v[210:211], v100 offset:13216
	ds_read_b64_tr_b16 v[212:213], v100 offset:8896
	ds_read_b64_tr_b16 v[214:215], v100 offset:13248
	ds_read_b64_tr_b16 v[216:217], v100 offset:8736
	ds_read_b64_tr_b16 v[218:219], v100 offset:13088
	ds_read_b64_tr_b16 v[220:221], v100 offset:8928
	ds_read_b64_tr_b16 v[222:223], v100 offset:13280
	s_waitcnt lgkmcnt(14)
	v_mfma_f32_16x16x32_bf16 v[80:83], v[192:195], v[108:111], v[80:83]
	s_waitcnt lgkmcnt(12)
	v_mfma_f32_16x16x32_bf16 v[60:63], v[196:199], v[108:111], v[60:63]
	s_waitcnt lgkmcnt(10)
	v_mfma_f32_16x16x32_bf16 v[64:67], v[200:203], v[108:111], v[64:67]
	s_waitcnt lgkmcnt(8)
	v_mfma_f32_16x16x32_bf16 v[72:75], v[204:207], v[108:111], v[72:75]
	s_waitcnt lgkmcnt(6)
	v_mfma_f32_16x16x32_bf16 v[68:71], v[208:211], v[108:111], v[68:71]
	s_waitcnt lgkmcnt(4)
	v_mfma_f32_16x16x32_bf16 v[56:59], v[212:215], v[108:111], v[56:59]
	s_waitcnt lgkmcnt(2)
	v_mfma_f32_16x16x32_bf16 v[76:79], v[216:219], v[108:111], v[76:79]
	s_waitcnt lgkmcnt(0)
	v_mfma_f32_16x16x32_bf16 v[52:55], v[220:223], v[108:111], v[52:55]

; #define LAS __attribute__((address_space(3)))
; __device__ __forceinline__ unsigned cvt_pk_bf16(float lo, float hi) { unsigned r; asm volatile("v_cvt_pk_bf16_f32 %0, %1, %2" : "=v"(r) : "v"(lo), "v"(hi)); return r; }
; __device__ __forceinline__ void attn_phase(LAS unsigned char* lds, const bf16_t* qkv, bf16_t* og, float* lse, int G, int bid) {
;     ...
;             for (int ks = 0; ks < 8; ++ks) {
;                 if (2 * ks + 1 >= wid && 2 * ks <= wid + 8 && (ks >= 4 || blk > 0)) {
;                     union { u32x4 u; bf16x8 b; } P;
;                     P.u.x = cvt_pk_bf16(sc[2 * ks][0], sc[2 * ks][1]); P.u.y = cvt_pk_bf16(sc[2 * ks][2], sc[2 * ks][3]);
;                     P.u.z = cvt_pk_bf16(sc[2 * ks + 1][0], sc[2 * ks + 1][1]); P.u.w = cvt_pk_bf16(sc[2 * ks + 1][2], sc[2 * ks + 1][3]);
;                     LAS unsigned char* vb = (ks < 4 ? Vp : Vc) + (32 * (ks & 3) + 4 * fq + (fr >> 2)) * KP + 8 * (fr & 3);
; #pragma unroll
;                     for (int dt = 0; dt < 8; ++dt) {
;                         const s16x4 v0 = __builtin_amdgcn_ds_read_tr16_b64_v4i16((LAS s16x4*)(vb + 32 * dt));
;                         const s16x4 v1 = __builtin_amdgcn_ds_read_tr16_b64_v4i16((LAS s16x4*)(vb + 16 * KP + 32 * dt));
;                         const bf16x8 vf = __builtin_shufflevector(v0, v1, 0, 1, 2, 3, 4, 5, 6, 7);
;                         o[dt] = __builtin_amdgcn_mfma_f32_16x16x32_bf16(vf, P.b, o[dt], 0, 0, 0);
;                     }
;                 }
.LBB0_1231:
	v_cvt_pk_bf16_f32 v88, v87, v88
	v_cvt_pk_bf16_f32 v89, v89, v90
	v_cvt_pk_bf16_f32 v90, v86, v91
	v_cvt_pk_bf16_f32 v91, v92, v93
	ds_read_b64_tr_b16 v[192:193], v0 offset:26112
	ds_read_b64_tr_b16 v[194:195], v0 offset:30464
	ds_read_b64_tr_b16 v[196:197], v0 offset:26176
	ds_read_b64_tr_b16 v[198:199], v0 offset:30528
	ds_read_b64_tr_b16 v[200:201], v0 offset:26208
	ds_read_b64_tr_b16 v[202:203], v0 offset:30560
	ds_read_b64_tr_b16 v[204:205], v0 offset:26240
	ds_read_b64_tr_b16 v[206:207], v0 offset:30592
	ds_read_b64_tr_b16 v[208:209], v0 offset:26272
	ds_read_b64_tr_b16 v[210:211], v0 offset:30624
	ds_read_b64_tr_b16 v[212:213], v0 offset:26304
	ds_read_b64_tr_b16 v[214:215], v0 offset:30656
	ds_read_b64_tr_b16 v[216:217], v0 offset:26144
	ds_read_b64_tr_b16 v[218:219], v0 offset:30496
	ds_read_b64_tr_b16 v[220:221], v0 offset:26336
	ds_read_b64_tr_b16 v[222:223], v0 offset:30688
	s_waitcnt lgkmcnt(14)
	v_mfma_f32_16x16x32_bf16 v[80:83], v[192:195], v[88:91], v[80:83]
	s_waitcnt lgkmcnt(12)
	v_mfma_f32_16x16x32_bf16 v[60:63], v[196:199], v[88:91], v[60:63]
	s_waitcnt lgkmcnt(10)
	v_mfma_f32_16x16x32_bf16 v[64:67], v[200:203], v[88:91], v[64:67]
	s_waitcnt lgkmcnt(8)
	v_mfma_f32_16x16x32_bf16 v[72:75], v[204:207], v[88:91], v[72:75]
	s_waitcnt lgkmcnt(6)
	v_mfma_f32_16x16x32_bf16 v[68:71], v[208:211], v[88:91], v[68:71]
	s_waitcnt lgkmcnt(4)
	v_mfma_f32_16x16x32_bf16 v[56:59], v[212:215], v[88:91], v[56:59]
	s_waitcnt lgkmcnt(2)
	v_mfma_f32_16x16x32_bf16 v[76:79], v[216:219], v[88:91], v[76:79]
	s_waitcnt lgkmcnt(0)
	v_mfma_f32_16x16x32_bf16 v[52:55], v[220:223], v[88:91], v[52:55]

; #define LAS __attribute__((address_space(3)))
; __device__ __forceinline__ unsigned cvt_pk_bf16(float lo, float hi) { unsigned r; asm volatile("v_cvt_pk_bf16_f32 %0, %1, %2" : "=v"(r) : "v"(lo), "v"(hi)); return r; }
; __device__ __forceinline__ void attn_phase(LAS unsigned char* lds, const bf16_t* qkv, bf16_t* og, float* lse, int G, int bid) {
;     ...
;             for (int ks = 0; ks < 8; ++ks) {
;                 if (2 * ks + 1 >= wid && 2 * ks <= wid + 8 && (ks >= 4 || blk > 0)) {
;                     union { u32x4 u; bf16x8 b; } P;
;                     P.u.x = cvt_pk_bf16(sc[2 * ks][0], sc[2 * ks][1]); P.u.y = cvt_pk_bf16(sc[2 * ks][2], sc[2 * ks][3]);
;                     P.u.z = cvt_pk_bf16(sc[2 * ks + 1][0], sc[2 * ks + 1][1]); P.u.w = cvt_pk_bf16(sc[2 * ks + 1][2], sc[2 * ks + 1][3]);
;                     LAS unsigned char* vb = (ks < 4 ? Vp : Vc) + (32 * (ks & 3) + 4 * fq + (fr >> 2)) * KP + 8 * (fr & 3);
; #pragma unroll
;                     for (int dt = 0; dt < 8; ++dt) {
;                         const s16x4 v0 = __builtin_amdgcn_ds_read_tr16_b64_v4i16((LAS s16x4*)(vb + 32 * dt));
;                         const s16x4 v1 = __builtin_amdgcn_ds_read_tr16_b64_v4i16((LAS s16x4*)(vb + 16 * KP + 32 * dt));
;                         const bf16x8 vf = __builtin_shufflevector(v0, v1, 0, 1, 2, 3, 4, 5, 6, 7);
;                         o[dt] = __builtin_amdgcn_mfma_f32_16x16x32_bf16(vf, P.b, o[dt], 0, 0, 0);
;                     }
;                 }
.LBB0_1236:
	v_cvt_pk_bf16_f32 v108, v172, v173
	v_cvt_pk_bf16_f32 v109, v174, v175
	v_cvt_pk_bf16_f32 v110, v171, v176
	v_cvt_pk_bf16_f32 v111, v177, v178
	ds_read_b64_tr_b16 v[192:193], v100 offset:17408
	ds_read_b64_tr_b16 v[194:195], v100 offset:21760
	ds_read_b64_tr_b16 v[196:197], v100 offset:17472
	ds_read_b64_tr_b16 v[198:199], v100 offset:21824
	ds_read_b64_tr_b16 v[200:201], v100 offset:17504
	ds_read_b64_tr_b16 v[202:203], v100 offset:21856
	ds_read_b64_tr_b16 v[204:205], v100 offset:17536
	ds_read_b64_tr_b16 v[206:207], v100 offset:21888
	ds_read_b64_tr_b16 v[208:209], v100 offset:17568
	ds_read_b64_tr_b16 v[210:211], v100 offset:21920
	ds_read_b64_tr_b16 v[212:213], v100 offset:17600
	ds_read_b64_tr_b16 v[214:215], v100 offset:21952
	ds_read_b64_tr_b16 v[216:217], v100 offset:17440
	ds_read_b64_tr_b16 v[218:219], v100 offset:21792
	ds_read_b64_tr_b16 v[220:221], v100 offset:17632
	ds_read_b64_tr_b16 v[222:223], v100 offset:21984
	s_waitcnt lgkmcnt(14)
	v_mfma_f32_16x16x32_bf16 v[80:83], v[192:195], v[108:111], v[80:83]
	s_waitcnt lgkmcnt(12)
	v_mfma_f32_16x16x32_bf16 v[60:63], v[196:199], v[108:111], v[60:63]
	s_waitcnt lgkmcnt(10)
	v_mfma_f32_16x16x32_bf16 v[64:67], v[200:203], v[108:111], v[64:67]
	s_waitcnt lgkmcnt(8)
	v_mfma_f32_16x16x32_bf16 v[72:75], v[204:207], v[108:111], v[72:75]
	s_waitcnt lgkmcnt(6)
	v_mfma_f32_16x16x32_bf16 v[68:71], v[208:211], v[108:111], v[68:71]
	s_waitcnt lgkmcnt(4)
	v_mfma_f32_16x16x32_bf16 v[56:59], v[212:215], v[108:111], v[56:59]
	s_waitcnt lgkmcnt(2)
	v_mfma_f32_16x16x32_bf16 v[76:79], v[216:219], v[108:111], v[76:79]
	s_waitcnt lgkmcnt(0)
	v_mfma_f32_16x16x32_bf16 v[52:55], v[220:223], v[108:111], v[52:55]
	s_and_b64 vcc, exec, s[30:31]
	s_cbranch_vccnz .LBB0_1227
.LBB0_1237:
	v_cvt_pk_bf16_f32 v108, v164, v165
	v_cvt_pk_bf16_f32 v109, v166, v167
	v_cvt_pk_bf16_f32 v110, v131, v168
	v_cvt_pk_bf16_f32 v111, v169, v170
	ds_read_b64_tr_b16 v[192:193], v100 offset:26112
	ds_read_b64_tr_b16 v[194:195], v100 offset:30464
	ds_read_b64_tr_b16 v[196:197], v100 offset:26176
	ds_read_b64_tr_b16 v[198:199], v100 offset:30528
	ds_read_b64_tr_b16 v[200:201], v100 offset:26208
	ds_read_b64_tr_b16 v[202:203], v100 offset:30560
	ds_read_b64_tr_b16 v[204:205], v100 offset:26240
	ds_read_b64_tr_b16 v[206:207], v100 offset:30592
	ds_read_b64_tr_b16 v[208:209], v100 offset:26272
	ds_read_b64_tr_b16 v[210:211], v100 offset:30624
	ds_read_b64_tr_b16 v[212:213], v100 offset:26304
	ds_read_b64_tr_b16 v[214:215], v100 offset:30656
	ds_read_b64_tr_b16 v[216:217], v100 offset:26144
	ds_read_b64_tr_b16 v[218:219], v100 offset:30496
	ds_read_b64_tr_b16 v[220:221], v100 offset:26336
	ds_read_b64_tr_b16 v[222:223], v100 offset:30688
	s_waitcnt lgkmcnt(14)
	v_mfma_f32_16x16x32_bf16 v[80:83], v[192:195], v[108:111], v[80:83]
	s_waitcnt lgkmcnt(12)
	v_mfma_f32_16x16x32_bf16 v[60:63], v[196:199], v[108:111], v[60:63]
	s_waitcnt lgkmcnt(10)
	v_mfma_f32_16x16x32_bf16 v[64:67], v[200:203], v[108:111], v[64:67]
	s_waitcnt lgkmcnt(8)
	v_mfma_f32_16x16x32_bf16 v[72:75], v[204:207], v[108:111], v[72:75]
	s_waitcnt lgkmcnt(6)
	v_mfma_f32_16x16x32_bf16 v[68:71], v[208:211], v[108:111], v[68:71]
	s_waitcnt lgkmcnt(4)
	v_mfma_f32_16x16x32_bf16 v[56:59], v[212:215], v[108:111], v[56:59]
	s_waitcnt lgkmcnt(2)
	v_mfma_f32_16x16x32_bf16 v[76:79], v[216:219], v[108:111], v[76:79]
	s_waitcnt lgkmcnt(0)
	v_mfma_f32_16x16x32_bf16 v[52:55], v[220:223], v[108:111], v[52:55]
	s_andn2_b64 vcc, exec, s[68:69]
	v_add_u32_e32 v0, s81, v156
	s_cbranch_vccnz .LBB0_1228
; #define LAS __attribute__((address_space(3)))
; __device__ __forceinline__ unsigned cvt_pk_bf16(float lo, float hi) { unsigned r; asm volatile("v_cvt_pk_bf16_f32 %0, %1, %2" : "=v"(r) : "v"(lo), "v"(hi)); return r; }
; __device__ __forceinline__ void attn_phase(LAS unsigned char* lds, const bf16_t* qkv, bf16_t* og, float* lse, int G, int bid) {
;     ...
;             for (int ks = 0; ks < 8; ++ks) {
;                 if (2 * ks + 1 >= wid && 2 * ks <= wid + 8 && (ks >= 4 || blk > 0)) {
;                     union { u32x4 u; bf16x8 b; } P;
;                     P.u.x = cvt_pk_bf16(sc[2 * ks][0], sc[2 * ks][1]); P.u.y = cvt_pk_bf16(sc[2 * ks][2], sc[2 * ks][3]);
;                     P.u.z = cvt_pk_bf16(sc[2 * ks + 1][0], sc[2 * ks + 1][1]); P.u.w = cvt_pk_bf16(sc[2 * ks + 1][2], sc[2 * ks + 1][3]);
;                     LAS unsigned char* vb = (ks < 4 ? Vp : Vc) + (32 * (ks & 3) + 4 * fq + (fr >> 2)) * KP + 8 * (fr & 3);
; #pragma unroll
;                     for (int dt = 0; dt < 8; ++dt) {
;                         const s16x4 v0 = __builtin_amdgcn_ds_read_tr16_b64_v4i16((LAS s16x4*)(vb + 32 * dt));
;                         const s16x4 v1 = __builtin_amdgcn_ds_read_tr16_b64_v4i16((LAS s16x4*)(vb + 16 * KP + 32 * dt));
;                         const bf16x8 vf = __builtin_shufflevector(v0, v1, 0, 1, 2, 3, 4, 5, 6, 7);
;                         o[dt] = __builtin_amdgcn_mfma_f32_16x16x32_bf16(vf, P.b, o[dt], 0, 0, 0);
;                     }
;                 }
.LBB0_1238:
	v_cvt_pk_bf16_f32 v100, v124, v125
	v_cvt_pk_bf16_f32 v101, v126, v127
	v_cvt_pk_bf16_f32 v102, v123, v128
	v_cvt_pk_bf16_f32 v103, v129, v130
	ds_read_b64_tr_b16 v[192:193], v0
	ds_read_b64_tr_b16 v[194:195], v0 offset:4352
	ds_read_b64_tr_b16 v[196:197], v0 offset:64
	ds_read_b64_tr_b16 v[198:199], v0 offset:4416
	ds_read_b64_tr_b16 v[200:201], v0 offset:96
	ds_read_b64_tr_b16 v[202:203], v0 offset:4448
	ds_read_b64_tr_b16 v[204:205], v0 offset:128
	ds_read_b64_tr_b16 v[206:207], v0 offset:4480
	ds_read_b64_tr_b16 v[208:209], v0 offset:160
	ds_read_b64_tr_b16 v[210:211], v0 offset:4512
	ds_read_b64_tr_b16 v[212:213], v0 offset:192
	ds_read_b64_tr_b16 v[214:215], v0 offset:4544
	ds_read_b64_tr_b16 v[216:217], v0 offset:32
	ds_read_b64_tr_b16 v[218:219], v0 offset:4384
	ds_read_b64_tr_b16 v[220:221], v0 offset:224
	ds_read_b64_tr_b16 v[222:223], v0 offset:4576
	s_waitcnt lgkmcnt(14)
	v_mfma_f32_16x16x32_bf16 v[80:83], v[192:195], v[100:103], v[80:83]
	s_waitcnt lgkmcnt(12)
	v_mfma_f32_16x16x32_bf16 v[60:63], v[196:199], v[100:103], v[60:63]
	s_waitcnt lgkmcnt(10)
	v_mfma_f32_16x16x32_bf16 v[64:67], v[200:203], v[100:103], v[64:67]
	s_waitcnt lgkmcnt(8)
	v_mfma_f32_16x16x32_bf16 v[72:75], v[204:207], v[100:103], v[72:75]
	s_waitcnt lgkmcnt(6)
	v_mfma_f32_16x16x32_bf16 v[68:71], v[208:211], v[100:103], v[68:71]
	s_waitcnt lgkmcnt(4)
	v_mfma_f32_16x16x32_bf16 v[56:59], v[212:215], v[100:103], v[56:59]
	s_waitcnt lgkmcnt(2)
	v_mfma_f32_16x16x32_bf16 v[76:79], v[216:219], v[100:103], v[76:79]
	s_waitcnt lgkmcnt(0)
	v_mfma_f32_16x16x32_bf16 v[52:55], v[220:223], v[100:103], v[52:55]
	s_andn2_b64 vcc, exec, s[92:93]
	s_cbranch_vccnz .LBB0_1229
.LBB0_1239:
	v_cvt_pk_bf16_f32 v100, v118, v119
	v_cvt_pk_bf16_f32 v101, v106, v107
	v_cvt_pk_bf16_f32 v102, v117, v120
	v_cvt_pk_bf16_f32 v103, v121, v122
	ds_read_b64_tr_b16 v[192:193], v0 offset:8704
	ds_read_b64_tr_b16 v[194:195], v0 offset:13056
	ds_read_b64_tr_b16 v[196:197], v0 offset:8768
	ds_read_b64_tr_b16 v[198:199], v0 offset:13120
	ds_read_b64_tr_b16 v[200:201], v0 offset:8800
	ds_read_b64_tr_b16 v[202:203], v0 offset:13152
	ds_read_b64_tr_b16 v[204:205], v0 offset:8832
	ds_read_b64_tr_b16 v[206:207], v0 offset:13184
	ds_read_b64_tr_b16 v[208:209], v0 offset:8864
	ds_read_b64_tr_b16 v[210:211], v0 offset:13216
	ds_read_b64_tr_b16 v[212:213], v0 offset:8896
	ds_read_b64_tr_b16 v[214:215], v0 offset:13248
	ds_read_b64_tr_b16 v[216:217], v0 offset:8736
	ds_read_b64_tr_b16 v[218:219], v0 offset:13088
	ds_read_b64_tr_b16 v[220:221], v0 offset:8928
	ds_read_b64_tr_b16 v[222:223], v0 offset:13280
	s_waitcnt lgkmcnt(14)
	v_mfma_f32_16x16x32_bf16 v[80:83], v[192:195], v[100:103], v[80:83]
	s_waitcnt lgkmcnt(12)
	v_mfma_f32_16x16x32_bf16 v[60:63], v[196:199], v[100:103], v[60:63]
	s_waitcnt lgkmcnt(10)
	v_mfma_f32_16x16x32_bf16 v[64:67], v[200:203], v[100:103], v[64:67]
	s_waitcnt lgkmcnt(8)
	v_mfma_f32_16x16x32_bf16 v[72:75], v[204:207], v[100:103], v[72:75]
	s_waitcnt lgkmcnt(6)
	v_mfma_f32_16x16x32_bf16 v[68:71], v[208:211], v[100:103], v[68:71]
	s_waitcnt lgkmcnt(4)
	v_mfma_f32_16x16x32_bf16 v[56:59], v[212:215], v[100:103], v[56:59]
	s_waitcnt lgkmcnt(2)
	v_mfma_f32_16x16x32_bf16 v[76:79], v[216:219], v[100:103], v[76:79]
	s_waitcnt lgkmcnt(0)
	v_mfma_f32_16x16x32_bf16 v[52:55], v[220:223], v[100:103], v[52:55]
	s_andn2_b64 vcc, exec, s[94:95]
	s_cbranch_vccnz .LBB0_1230
.LBB0_1240:
	v_cvt_pk_bf16_f32 v98, v97, v98
	v_cvt_pk_bf16_f32 v99, v99, v104
	v_cvt_pk_bf16_f32 v100, v96, v105
	v_cvt_pk_bf16_f32 v101, v94, v95
	ds_read_b64_tr_b16 v[192:193], v0 offset:17408
	ds_read_b64_tr_b16 v[194:195], v0 offset:21760
	ds_read_b64_tr_b16 v[196:197], v0 offset:17472
	ds_read_b64_tr_b16 v[198:199], v0 offset:21824
	ds_read_b64_tr_b16 v[200:201], v0 offset:17504
	ds_read_b64_tr_b16 v[202:203], v0 offset:21856
	ds_read_b64_tr_b16 v[204:205], v0 offset:17536
	ds_read_b64_tr_b16 v[206:207], v0 offset:21888
	ds_read_b64_tr_b16 v[208:209], v0 offset:17568
	ds_read_b64_tr_b16 v[210:211], v0 offset:21920
	ds_read_b64_tr_b16 v[212:213], v0 offset:17600
	ds_read_b64_tr_b16 v[214:215], v0 offset:21952
	ds_read_b64_tr_b16 v[216:217], v0 offset:17440
	ds_read_b64_tr_b16 v[218:219], v0 offset:21792
	ds_read_b64_tr_b16 v[220:221], v0 offset:17632
	ds_read_b64_tr_b16 v[222:223], v0 offset:21984
	s_waitcnt lgkmcnt(14)
	v_mfma_f32_16x16x32_bf16 v[80:83], v[192:195], v[98:101], v[80:83]
	s_waitcnt lgkmcnt(12)
	v_mfma_f32_16x16x32_bf16 v[60:63], v[196:199], v[98:101], v[60:63]
	s_waitcnt lgkmcnt(10)
	v_mfma_f32_16x16x32_bf16 v[64:67], v[200:203], v[98:101], v[64:67]
	s_waitcnt lgkmcnt(8)
	v_mfma_f32_16x16x32_bf16 v[72:75], v[204:207], v[98:101], v[72:75]
	s_waitcnt lgkmcnt(6)
	v_mfma_f32_16x16x32_bf16 v[68:71], v[208:211], v[98:101], v[68:71]
	s_waitcnt lgkmcnt(4)
	v_mfma_f32_16x16x32_bf16 v[56:59], v[212:215], v[98:101], v[56:59]
	s_waitcnt lgkmcnt(2)
	v_mfma_f32_16x16x32_bf16 v[76:79], v[216:219], v[98:101], v[76:79]
	s_waitcnt lgkmcnt(0)
	v_mfma_f32_16x16x32_bf16 v[52:55], v[220:223], v[98:101], v[52:55]
	s_andn2_b64 vcc, exec, s[96:97]
	s_cbranch_vccz .LBB0_1231
	s_branch .LBB0_1232
